# attention: first 6 K-fragment LDS reads of each hot step issued before the loop-head global-load address math
# speedup vs baseline: 1.0036x; 1.0036x over previous
.LBB0_941:
	s_add_i32 s40, s73, -3
	s_cmp_lt_i32 s40, s72
	s_cbranch_scc1 .Latt_hotA_pre
	s_add_i32 s10, s73, -1
	s_min_i32 s66, s10, s33
	v_mad_u64_u32 v[2:3], s[10:11], v196, s66, 0
	v_lshl_add_u64 v[2:3], v[2:3], 1, v[192:193]
	s_add_i32 s75, s73, -2
	global_load_dwordx4 v[184:187], v[2:3], off
	v_mad_u64_u32 v[2:3], s[10:11], v195, s66, 0
	s_min_i32 s40, s75, s33
	v_lshl_add_u64 v[2:3], v[2:3], 1, v[202:203]
	s_lshl_b64 s[10:11], s[40:41], 7
	global_load_dwordx4 v[180:183], v[2:3], off
	v_lshl_add_u64 v[2:3], v[200:201], 0, s[10:11]
	global_load_dwordx4 v[188:191], v[2:3], off
	s_add_i32 s40, s73, -3
	s_cmp_lt_i32 s40, s72
	s_cselect_b64 s[70:71], -1, 0
	s_cmp_ge_i32 s40, s72
	s_mov_b64 s[10:11], -1
	s_cbranch_scc1 .LBB0_949
	s_andn2_b64 vcc, exec, s[10:11]
	s_cbranch_vccz .LBB0_952

; __device__ __forceinline__ void attn_unit(LAS unsigned char* lds, const bf16_t* Qrow0, int nqw, int limbase, bool prompt, size_t kv0, int NT, int h,
;                                           const bf16_t* KN, const bf16_t* KR, const bf16_t* VVt, bf16_t* Yrow0, unsigned* tkctr, int& tick) {
;     ...
;     for (int t = 0; t < NT; t += 2) {
;         ATT_ITER(t, ak0, ak1, av, bk0, bk1, bv);
;         if (t + 1 < NT) ATT_ITER(t + 1, bk0, bk1, bv, ak0, ak1, av);
.Latt_barA:
	s_waitcnt lgkmcnt(0)
	s_barrier
	s_cmp_ge_i32 s40, s74
	s_cbranch_scc1 .LBB0_953
	s_cmp_lt_i32 s75, s72
	s_cbranch_scc1 .Latt_hotB_pre
	s_min_i32 s40, s73, s33
	v_mad_u64_u32 v[2:3], s[10:11], v196, s40, 0
	v_lshl_add_u64 v[2:3], v[2:3], 1, v[192:193]
	s_mov_b32 s67, s41
	global_load_dwordx4 v[168:171], v[2:3], off
	v_mad_u64_u32 v[2:3], s[10:11], v195, s40, 0
	v_lshl_add_u64 v[2:3], v[2:3], 1, v[202:203]
	s_lshl_b64 s[10:11], s[66:67], 7
	global_load_dwordx4 v[172:175], v[2:3], off
	v_lshl_add_u64 v[2:3], v[200:201], 0, s[10:11]
	global_load_dwordx4 v[176:179], v[2:3], off
	s_cmp_ge_i32 s75, s72
	s_mov_b64 s[10:11], -1
	s_cbranch_scc1 .LBB0_954
	s_andn2_b64 vcc, exec, s[10:11]
	s_cbranch_vccz .LBB0_957

; #define LAS __attribute__((address_space(3)))
; __device__ __forceinline__ float max3f(float a, float b, float c) { float r; asm("v_max3_f32 %0, %1, %2, %3" : "=v"(r) : "v"(a), "v"(b), "v"(c)); return r; }
; template <bool QK, bool SM>
; __device__ __forceinline__ void attn_step(const LAS unsigned char* kb, const LAS unsigned char* vbp, const bf16x8 (&qr)[6],
;                                           f32x16& s0, f32x16& s1, f32x16& o0, f32x16& o1, float& mrow, float& lsum) {
;     ...
;         for (int s = 0; s < 6; ++s) { const bf16x8 ka = *(const LAS bf16x8*)(kb + s * 32), kc = *(const LAS bf16x8*)(kb + 32 * KPITCH + s * 32);
;             n0 = __builtin_amdgcn_mfma_f32_32x32x16_bf16(ka, qr[s], n0, 0, 0, 0); n1 = __builtin_amdgcn_mfma_f32_32x32x16_bf16(kc, qr[s], n1, 0, 0, 0); }
;     }
;     if constexpr (SM) {
;         float mx = max3f(s0[0], s1[0], s0[1]); mx = max3f(mx, s1[1], s0[2]); float my = max3f(s1[2], s0[3], s1[3]);
; #pragma unroll
;         for (int r = 4; r < 16; r += 4) { mx = max3f(mx, s0[r], s1[r]); my = max3f(my, s0[r + 1], s1[r + 1]); mx = max3f(mx, s0[r + 2], s1[r + 2]); my = max3f(my, s0[r + 3], s1[r + 3]); }
;         mx = fmaxf(mx, my);
;         { const auto rr = __builtin_amdgcn_permlane32_swap(__float_as_uint(mx), __float_as_uint(mx), false, false); mx = fmaxf(__uint_as_float(rr[0]), __uint_as_float(rr[1])); }
;         const float mnew = fmaxf(mrow, mx), alpha = __builtin_amdgcn_exp2f(mrow - mnew); mrow = mnew;
.Latt_A_after6:
	s_waitcnt lgkmcnt(5)
	v_mfma_f32_32x32x16_bf16 v[112:127], v[2:5], v[164:167], v[218:233]
	ds_read_b128 v[100:103], v213 offset:20032
	ds_read_b128 v[104:107], v213 offset:20064
	ds_read_b128 v[92:95], v213 offset:13440
	ds_read_b128 v[108:111], v213 offset:13472
	ds_read_b128 v[6:9], v213 offset:20096
	ds_read_b128 v[2:5], v213 offset:20128
	v_max3_f32 v0, v48, v16, v49
	v_max3_f32 v0, v0, v17, v50
	v_max3_f32 v0, v0, v52, v20
	s_waitcnt lgkmcnt(10)
	v_mfma_f32_32x32x16_bf16 v[112:127], v[10:13], v[160:163], v[112:127]
	v_max3_f32 v10, v18, v51, v19
	v_max3_f32 v0, v0, v54, v22
	v_max3_f32 v10, v10, v53, v21
	v_max3_f32 v0, v0, v56, v24
	v_max3_f32 v10, v10, v55, v23
	s_waitcnt lgkmcnt(7)
	v_mfma_f32_32x32x16_bf16 v[112:127], v[84:87], v[156:159], v[112:127]
	v_max3_f32 v10, v10, v57, v25
	v_max3_f32 v0, v0, v58, v26
	v_max3_f32 v10, v10, v59, v27
	v_max3_f32 v0, v0, v60, v28
	v_max3_f32 v10, v10, v61, v29
	s_waitcnt lgkmcnt(6)
	v_mfma_f32_32x32x16_bf16 v[112:127], v[88:91], v[152:155], v[112:127]
	v_max3_f32 v10, v10, v63, v31
	v_max3_f32 v0, v0, v62, v30
	v_max_f32_e32 v10, v10, v10
	v_max_f32_e32 v0, v0, v0
	v_max_f32_e32 v0, v0, v10
	v_mov_b32_e32 v10, v0
	s_waitcnt lgkmcnt(3)
	v_mfma_f32_32x32x16_bf16 v[112:127], v[92:95], v[148:151], v[112:127]
	v_permlane32_swap_b32_e32 v0, v10
	v_max_f32_e32 v0, v0, v10
	v_sub_f32_e32 v10, v0, v206
	v_cmp_lt_f32_e32 vcc, 0x41000000, v10
	v_mov_b32_e32 v208, v206
	s_nop 0
	s_cbranch_vccnz .Latt_slowA

; #define LAS __attribute__((address_space(3)))
; template <bool QK, bool SM>
; __device__ __forceinline__ void attn_step(const LAS unsigned char* kb, const LAS unsigned char* vbp, const bf16x8 (&qr)[6],
;                                           f32x16& s0, f32x16& s1, f32x16& o0, f32x16& o1, float& mrow, float& lsum) {
;     ...
;         for (int s = 0; s < 6; ++s) { const bf16x8 ka = *(const LAS bf16x8*)(kb + s * 32), kc = *(const LAS bf16x8*)(kb + 32 * KPITCH + s * 32);
.Latt_hotA_pre:
	ds_read_b128 v[2:5], v213 offset:13312
	ds_read_b128 v[10:13], v213 offset:13344
	ds_read_b128 v[80:83], v213 offset:19968
	ds_read_b128 v[96:99], v213 offset:20000
	ds_read_b128 v[84:87], v213 offset:13376
	ds_read_b128 v[88:91], v213 offset:13408
	s_add_i32 s10, s73, -1
	s_min_i32 s66, s10, s33
	v_mad_u64_u32 v[136:137], s[10:11], v196, s66, 0
	v_lshl_add_u64 v[136:137], v[136:137], 1, v[192:193]
	s_add_i32 s75, s73, -2
	global_load_dwordx4 v[184:187], v[136:137], off
	v_mad_u64_u32 v[136:137], s[10:11], v195, s66, 0
	s_min_i32 s40, s75, s33
	v_lshl_add_u64 v[136:137], v[136:137], 1, v[202:203]
	s_lshl_b64 s[10:11], s[40:41], 7
	global_load_dwordx4 v[180:183], v[136:137], off
	v_lshl_add_u64 v[136:137], v[200:201], 0, s[10:11]
	global_load_dwordx4 v[188:191], v[136:137], off
	s_add_i32 s40, s73, -3
	s_mov_b64 s[70:71], -1
	s_branch .Latt_A_after6
.Latt_hotB_pre:
	ds_read_b128 v[2:5], v213
	ds_read_b128 v[10:13], v213 offset:32
	ds_read_b128 v[14:17], v213 offset:6656
	ds_read_b128 v[96:99], v213 offset:6688
	ds_read_b128 v[18:21], v213 offset:64
	ds_read_b128 v[22:25], v213 offset:96
	s_min_i32 s40, s73, s33
	v_mad_u64_u32 v[136:137], s[10:11], v196, s40, 0
	v_lshl_add_u64 v[136:137], v[136:137], 1, v[192:193]
	s_mov_b32 s67, s41
	global_load_dwordx4 v[168:171], v[136:137], off
	v_mad_u64_u32 v[136:137], s[10:11], v195, s40, 0
	v_lshl_add_u64 v[136:137], v[136:137], 1, v[202:203]
	s_lshl_b64 s[10:11], s[66:67], 7
	global_load_dwordx4 v[172:175], v[136:137], off
	v_lshl_add_u64 v[136:137], v[200:201], 0, s[10:11]
	global_load_dwordx4 v[176:179], v[136:137], off
	s_branch .Latt_B_after6

; #define LAS __attribute__((address_space(3)))
; template <bool QK, bool SM>
; __device__ __forceinline__ void attn_step(const LAS unsigned char* kb, const LAS unsigned char* vbp, const bf16x8 (&qr)[6],
;                                           f32x16& s0, f32x16& s1, f32x16& o0, f32x16& o1, float& mrow, float& lsum) {
;     ...
;         for (int s = 0; s < 6; ++s) { const bf16x8 ka = *(const LAS bf16x8*)(kb + s * 32), kc = *(const LAS bf16x8*)(kb + 32 * KPITCH + s * 32);
;             n0 = __builtin_amdgcn_mfma_f32_32x32x16_bf16(ka, qr[s], n0, 0, 0, 0); n1 = __builtin_amdgcn_mfma_f32_32x32x16_bf16(kc, qr[s], n1, 0, 0, 0); }
.Latt_B_after6:
	s_waitcnt lgkmcnt(5)
	v_mfma_f32_32x32x16_bf16 v[48:63], v[2:5], v[164:167], v[218:233]

; __device__ __forceinline__ float max3f(float a, float b, float c) { float r; asm("v_max3_f32 %0, %1, %2, %3" : "=v"(r) : "v"(a), "v"(b), "v"(c)); return r; }
; template <bool QK, bool SM>
; __device__ __forceinline__ void attn_step(const LAS unsigned char* kb, const LAS unsigned char* vbp, const bf16x8 (&qr)[6],
;                                           f32x16& s0, f32x16& s1, f32x16& o0, f32x16& o1, float& mrow, float& lsum) {
;     ...
;         float mx = max3f(s0[0], s1[0], s0[1]); mx = max3f(mx, s1[1], s0[2]); float my = max3f(s1[2], s0[3], s1[3]);
	v_max3_f32 v0, v112, v80, v113

; #define LAS __attribute__((address_space(3)))
; template <bool QK, bool SM>
; __device__ __forceinline__ void attn_step(const LAS unsigned char* kb, const LAS unsigned char* vbp, const bf16x8 (&qr)[6],
;                                           f32x16& s0, f32x16& s1, f32x16& o0, f32x16& o1, float& mrow, float& lsum) {
;     ...
;         for (int s = 0; s < 6; ++s) { const bf16x8 ka = *(const LAS bf16x8*)(kb + s * 32), kc = *(const LAS bf16x8*)(kb + 32 * KPITCH + s * 32);
	ds_read_b128 v[100:103], v213 offset:6720
	ds_read_b128 v[104:107], v213 offset:6752
	ds_read_b128 v[26:29], v213 offset:128
	ds_read_b128 v[108:111], v213 offset:160
	ds_read_b128 v[6:9], v213 offset:6784
	ds_read_b128 v[2:5], v213 offset:6816

; __device__ __forceinline__ float max3f(float a, float b, float c) { float r; asm("v_max3_f32 %0, %1, %2, %3" : "=v"(r) : "v"(a), "v"(b), "v"(c)); return r; }
; template <bool QK, bool SM>
; __device__ __forceinline__ void attn_step(const LAS unsigned char* kb, const LAS unsigned char* vbp, const bf16x8 (&qr)[6],
;                                           f32x16& s0, f32x16& s1, f32x16& o0, f32x16& o1, float& mrow, float& lsum) {
;     ...
;         float mx = max3f(s0[0], s1[0], s0[1]); mx = max3f(mx, s1[1], s0[2]); float my = max3f(s1[2], s0[3], s1[3]);
; #pragma unroll
;         for (int r = 4; r < 16; r += 4) { mx = max3f(mx, s0[r], s1[r]); my = max3f(my, s0[r + 1], s1[r + 1]); mx = max3f(mx, s0[r + 2], s1[r + 2]); my = max3f(my, s0[r + 3], s1[r + 3]); }
	v_max3_f32 v0, v0, v81, v114

	v_add_u32_e32 v132, v214, v204

; __device__ __forceinline__ float max3f(float a, float b, float c) { float r; asm("v_max3_f32 %0, %1, %2, %3" : "=v"(r) : "v"(a), "v"(b), "v"(c)); return r; }
; template <bool QK, bool SM>
; __device__ __forceinline__ void attn_step(const LAS unsigned char* kb, const LAS unsigned char* vbp, const bf16x8 (&qr)[6],
;                                           f32x16& s0, f32x16& s1, f32x16& o0, f32x16& o1, float& mrow, float& lsum) {
;     ...
;         for (int r = 4; r < 16; r += 4) { mx = max3f(mx, s0[r], s1[r]); my = max3f(my, s0[r + 1], s1[r + 1]); mx = max3f(mx, s0[r + 2], s1[r + 2]); my = max3f(my, s0[r + 3], s1[r + 3]); }
	v_max3_f32 v0, v0, v116, v84


; __device__ __forceinline__ float max3f(float a, float b, float c) { float r; asm("v_max3_f32 %0, %1, %2, %3" : "=v"(r) : "v"(a), "v"(b), "v"(c)); return r; }
; template <bool QK, bool SM>
; __device__ __forceinline__ void attn_step(const LAS unsigned char* kb, const LAS unsigned char* vbp, const bf16x8 (&qr)[6],
;                                           f32x16& s0, f32x16& s1, f32x16& o0, f32x16& o1, float& mrow, float& lsum) {
;     ...
;         for (int r = 4; r < 16; r += 4) { mx = max3f(mx, s0[r], s1[r]); my = max3f(my, s0[r + 1], s1[r + 1]); mx = max3f(mx, s0[r + 2], s1[r + 2]); my = max3f(my, s0[r + 3], s1[r + 3]); }
	v_max3_f32 v0, v0, v118, v86

; template <bool QK, bool SM>
; __device__ __forceinline__ void attn_step(const LAS unsigned char* kb, const LAS unsigned char* vbp, const bf16x8 (&qr)[6],
;                                           f32x16& s0, f32x16& s1, f32x16& o0, f32x16& o1, float& mrow, float& lsum) {
;     ...
;             n0 = __builtin_amdgcn_mfma_f32_32x32x16_bf16(ka, qr[s], n0, 0, 0, 0); n1 = __builtin_amdgcn_mfma_f32_32x32x16_bf16(kc, qr[s], n1, 0, 0, 0); }
	s_waitcnt lgkmcnt(10)
	v_mfma_f32_32x32x16_bf16 v[48:63], v[10:13], v[160:163], v[48:63]

; __device__ __forceinline__ float max3f(float a, float b, float c) { float r; asm("v_max3_f32 %0, %1, %2, %3" : "=v"(r) : "v"(a), "v"(b), "v"(c)); return r; }
; template <bool QK, bool SM>
; __device__ __forceinline__ void attn_step(const LAS unsigned char* kb, const LAS unsigned char* vbp, const bf16x8 (&qr)[6],
;                                           f32x16& s0, f32x16& s1, f32x16& o0, f32x16& o1, float& mrow, float& lsum) {
;     ...
;         float mx = max3f(s0[0], s1[0], s0[1]); mx = max3f(mx, s1[1], s0[2]); float my = max3f(s1[2], s0[3], s1[3]);
; #pragma unroll
;         for (int r = 4; r < 16; r += 4) { mx = max3f(mx, s0[r], s1[r]); my = max3f(my, s0[r + 1], s1[r + 1]); mx = max3f(mx, s0[r + 2], s1[r + 2]); my = max3f(my, s0[r + 3], s1[r + 3]); }
	v_max3_f32 v10, v82, v115, v83


; __device__ __forceinline__ float max3f(float a, float b, float c) { float r; asm("v_max3_f32 %0, %1, %2, %3" : "=v"(r) : "v"(a), "v"(b), "v"(c)); return r; }
; template <bool QK, bool SM>
; __device__ __forceinline__ void attn_step(const LAS unsigned char* kb, const LAS unsigned char* vbp, const bf16x8 (&qr)[6],
;                                           f32x16& s0, f32x16& s1, f32x16& o0, f32x16& o1, float& mrow, float& lsum) {
;     ...
;         for (int r = 4; r < 16; r += 4) { mx = max3f(mx, s0[r], s1[r]); my = max3f(my, s0[r + 1], s1[r + 1]); mx = max3f(mx, s0[r + 2], s1[r + 2]); my = max3f(my, s0[r + 3], s1[r + 3]); }
	v_max3_f32 v0, v0, v120, v88


; __device__ __forceinline__ float max3f(float a, float b, float c) { float r; asm("v_max3_f32 %0, %1, %2, %3" : "=v"(r) : "v"(a), "v"(b), "v"(c)); return r; }
; template <bool QK, bool SM>
; __device__ __forceinline__ void attn_step(const LAS unsigned char* kb, const LAS unsigned char* vbp, const bf16x8 (&qr)[6],
;                                           f32x16& s0, f32x16& s1, f32x16& o0, f32x16& o1, float& mrow, float& lsum) {
;     ...
;         for (int r = 4; r < 16; r += 4) { mx = max3f(mx, s0[r], s1[r]); my = max3f(my, s0[r + 1], s1[r + 1]); mx = max3f(mx, s0[r + 2], s1[r + 2]); my = max3f(my, s0[r + 3], s1[r + 3]); }
	v_max3_f32 v10, v10, v117, v85


; __device__ __forceinline__ float max3f(float a, float b, float c) { float r; asm("v_max3_f32 %0, %1, %2, %3" : "=v"(r) : "v"(a), "v"(b), "v"(c)); return r; }
; template <bool QK, bool SM>
; __device__ __forceinline__ void attn_step(const LAS unsigned char* kb, const LAS unsigned char* vbp, const bf16x8 (&qr)[6],
;                                           f32x16& s0, f32x16& s1, f32x16& o0, f32x16& o1, float& mrow, float& lsum) {
;     ...
;         for (int r = 4; r < 16; r += 4) { mx = max3f(mx, s0[r], s1[r]); my = max3f(my, s0[r + 1], s1[r + 1]); mx = max3f(mx, s0[r + 2], s1[r + 2]); my = max3f(my, s0[r + 3], s1[r + 3]); }
	v_max3_f32 v0, v0, v122, v90


; __device__ __forceinline__ float max3f(float a, float b, float c) { float r; asm("v_max3_f32 %0, %1, %2, %3" : "=v"(r) : "v"(a), "v"(b), "v"(c)); return r; }
; template <bool QK, bool SM>
; __device__ __forceinline__ void attn_step(const LAS unsigned char* kb, const LAS unsigned char* vbp, const bf16x8 (&qr)[6],
;                                           f32x16& s0, f32x16& s1, f32x16& o0, f32x16& o1, float& mrow, float& lsum) {
;     ...
;         for (int r = 4; r < 16; r += 4) { mx = max3f(mx, s0[r], s1[r]); my = max3f(my, s0[r + 1], s1[r + 1]); mx = max3f(mx, s0[r + 2], s1[r + 2]); my = max3f(my, s0[r + 3], s1[r + 3]); }
	v_max3_f32 v10, v10, v119, v87

; template <bool QK, bool SM>
; __device__ __forceinline__ void attn_step(const LAS unsigned char* kb, const LAS unsigned char* vbp, const bf16x8 (&qr)[6],
;                                           f32x16& s0, f32x16& s1, f32x16& o0, f32x16& o1, float& mrow, float& lsum) {
;     ...
;             n0 = __builtin_amdgcn_mfma_f32_32x32x16_bf16(ka, qr[s], n0, 0, 0, 0); n1 = __builtin_amdgcn_mfma_f32_32x32x16_bf16(kc, qr[s], n1, 0, 0, 0); }
	s_waitcnt lgkmcnt(7)
	v_mfma_f32_32x32x16_bf16 v[48:63], v[18:21], v[156:159], v[48:63]

; __device__ __forceinline__ float max3f(float a, float b, float c) { float r; asm("v_max3_f32 %0, %1, %2, %3" : "=v"(r) : "v"(a), "v"(b), "v"(c)); return r; }
; template <bool QK, bool SM>
; __device__ __forceinline__ void attn_step(const LAS unsigned char* kb, const LAS unsigned char* vbp, const bf16x8 (&qr)[6],
;                                           f32x16& s0, f32x16& s1, f32x16& o0, f32x16& o1, float& mrow, float& lsum) {
;     ...
;         for (int r = 4; r < 16; r += 4) { mx = max3f(mx, s0[r], s1[r]); my = max3f(my, s0[r + 1], s1[r + 1]); mx = max3f(mx, s0[r + 2], s1[r + 2]); my = max3f(my, s0[r + 3], s1[r + 3]); }
	v_max3_f32 v10, v10, v121, v89


; __device__ __forceinline__ float max3f(float a, float b, float c) { float r; asm("v_max3_f32 %0, %1, %2, %3" : "=v"(r) : "v"(a), "v"(b), "v"(c)); return r; }
; template <bool QK, bool SM>
; __device__ __forceinline__ void attn_step(const LAS unsigned char* kb, const LAS unsigned char* vbp, const bf16x8 (&qr)[6],
;                                           f32x16& s0, f32x16& s1, f32x16& o0, f32x16& o1, float& mrow, float& lsum) {
;     ...
;         for (int r = 4; r < 16; r += 4) { mx = max3f(mx, s0[r], s1[r]); my = max3f(my, s0[r + 1], s1[r + 1]); mx = max3f(mx, s0[r + 2], s1[r + 2]); my = max3f(my, s0[r + 3], s1[r + 3]); }
	v_max3_f32 v0, v0, v124, v92


; __device__ __forceinline__ float max3f(float a, float b, float c) { float r; asm("v_max3_f32 %0, %1, %2, %3" : "=v"(r) : "v"(a), "v"(b), "v"(c)); return r; }
; template <bool QK, bool SM>
; __device__ __forceinline__ void attn_step(const LAS unsigned char* kb, const LAS unsigned char* vbp, const bf16x8 (&qr)[6],
;                                           f32x16& s0, f32x16& s1, f32x16& o0, f32x16& o1, float& mrow, float& lsum) {
;     ...
;         for (int r = 4; r < 16; r += 4) { mx = max3f(mx, s0[r], s1[r]); my = max3f(my, s0[r + 1], s1[r + 1]); mx = max3f(mx, s0[r + 2], s1[r + 2]); my = max3f(my, s0[r + 3], s1[r + 3]); }
	v_max3_f32 v10, v10, v123, v91


; __device__ __forceinline__ float max3f(float a, float b, float c) { float r; asm("v_max3_f32 %0, %1, %2, %3" : "=v"(r) : "v"(a), "v"(b), "v"(c)); return r; }
; template <bool QK, bool SM>
; __device__ __forceinline__ void attn_step(const LAS unsigned char* kb, const LAS unsigned char* vbp, const bf16x8 (&qr)[6],
;                                           f32x16& s0, f32x16& s1, f32x16& o0, f32x16& o1, float& mrow, float& lsum) {
;     ...
;         for (int r = 4; r < 16; r += 4) { mx = max3f(mx, s0[r], s1[r]); my = max3f(my, s0[r + 1], s1[r + 1]); mx = max3f(mx, s0[r + 2], s1[r + 2]); my = max3f(my, s0[r + 3], s1[r + 3]); }
	v_max3_f32 v0, v0, v126, v94


; __device__ __forceinline__ float max3f(float a, float b, float c) { float r; asm("v_max3_f32 %0, %1, %2, %3" : "=v"(r) : "v"(a), "v"(b), "v"(c)); return r; }
; template <bool QK, bool SM>
; __device__ __forceinline__ void attn_step(const LAS unsigned char* kb, const LAS unsigned char* vbp, const bf16x8 (&qr)[6],
;                                           f32x16& s0, f32x16& s1, f32x16& o0, f32x16& o1, float& mrow, float& lsum) {
;     ...
;         for (int r = 4; r < 16; r += 4) { mx = max3f(mx, s0[r], s1[r]); my = max3f(my, s0[r + 1], s1[r + 1]); mx = max3f(mx, s0[r + 2], s1[r + 2]); my = max3f(my, s0[r + 3], s1[r + 3]); }
	v_max3_f32 v10, v10, v125, v93

; template <bool QK, bool SM>
; __device__ __forceinline__ void attn_step(const LAS unsigned char* kb, const LAS unsigned char* vbp, const bf16x8 (&qr)[6],
;                                           f32x16& s0, f32x16& s1, f32x16& o0, f32x16& o1, float& mrow, float& lsum) {
;     ...
;             n0 = __builtin_amdgcn_mfma_f32_32x32x16_bf16(ka, qr[s], n0, 0, 0, 0); n1 = __builtin_amdgcn_mfma_f32_32x32x16_bf16(kc, qr[s], n1, 0, 0, 0); }
	s_waitcnt lgkmcnt(6)
	v_mfma_f32_32x32x16_bf16 v[48:63], v[22:25], v[152:155], v[48:63]

; __device__ __forceinline__ float max3f(float a, float b, float c) { float r; asm("v_max3_f32 %0, %1, %2, %3" : "=v"(r) : "v"(a), "v"(b), "v"(c)); return r; }
; template <bool QK, bool SM>
; __device__ __forceinline__ void attn_step(const LAS unsigned char* kb, const LAS unsigned char* vbp, const bf16x8 (&qr)[6],
;                                           f32x16& s0, f32x16& s1, f32x16& o0, f32x16& o1, float& mrow, float& lsum) {
;     ...
;         for (int r = 4; r < 16; r += 4) { mx = max3f(mx, s0[r], s1[r]); my = max3f(my, s0[r + 1], s1[r + 1]); mx = max3f(mx, s0[r + 2], s1[r + 2]); my = max3f(my, s0[r + 3], s1[r + 3]); }
	v_max3_f32 v10, v10, v127, v95

; template <bool QK, bool SM>
; __device__ __forceinline__ void attn_step(const LAS unsigned char* kb, const LAS unsigned char* vbp, const bf16x8 (&qr)[6],
;                                           f32x16& s0, f32x16& s1, f32x16& o0, f32x16& o1, float& mrow, float& lsum) {
;     ...
;         mx = fmaxf(mx, my);
;         { const auto rr = __builtin_amdgcn_permlane32_swap(__float_as_uint(mx), __float_as_uint(mx), false, false); mx = fmaxf(__uint_as_float(rr[0]), __uint_as_float(rr[1])); }
;         const float mnew = fmaxf(mrow, mx), alpha = __builtin_amdgcn_exp2f(mrow - mnew); mrow = mnew;
	v_max_f32_e32 v0, v0, v0
	v_max_f32_e32 v10, v10, v10
	v_max_f32_e32 v0, v0, v10
	v_mov_b32_e32 v10, v0
	s_nop 1
	v_permlane32_swap_b32_e32 v0, v10
	v_max_f32_e32 v0, v0, v10
	v_sub_f32_e32 v10, v0, v208
	v_cmp_lt_f32_e32 vcc, 0x41000000, v10
	v_mov_b32_e32 v206, v208
	s_nop 0
	s_cbranch_vccnz .Latt_slowB
